# sel loop: all waves issue next K-fragment LDS reads before the deferred softmax+PV; bias1 loads pipelined in prologue
# baseline (speedup 1.0000x reference)
; __global__ void __launch_bounds__(512, 2) fwd_megakernel(Args args) {
;     ...
;         for (int it = bx; it < 64; it += G) {
;             const int l = it >> 5, isv = (it >> 4) & 1, ng = it & 15, col = tid & 15, sl = tid >> 4;
;             const float* pos = args.in[isv ? 11 : 10] + (size_t)l * 2048 + sl * 64; const float* w1 = args.in[isv ? 14 : 12] + (size_t)l * 2048 * 256 + (size_t)sl * 64 * 256 + ng * 16 + col;
;             float a = 0.f;
; #pragma unroll 16
;             for (int k = 0; k < 64; ++k) a += pos[k] * w1[(size_t)k * 256];
.LBB0_193:
	s_bfe_u32 s17, s16, 0x10004
	s_lshl_b32 s9, s17, 3
	s_load_dwordx2 s[10:11], s[0:1], s9 offset:0x50
	s_lshl_b32 s8, s2, 2
	s_and_b32 s20, s8, 0x3c0
	s_ashr_i32 s8, s16, 5
	s_ashr_i32 s9, s8, 31
	s_lshl_b64 s[18:19], s[8:9], 13
	s_waitcnt lgkmcnt(0)
	s_add_u32 s10, s10, s18
	s_addc_u32 s11, s11, s19
	s_cmp_eq_u32 s17, 0
	s_cselect_b32 s18, s12, 0x70
	s_add_u32 s18, s0, s18
	s_addc_u32 s19, s1, 0
	s_load_dwordx2 s[18:19], s[18:19], 0x0
	v_lshl_add_u64 v[6:7], v[2:3], 2, s[10:11]
	s_lshl_b64 s[10:11], s[8:9], 21
	s_or_b32 s10, s10, s20
	v_mov_b32_e32 v12, 0
	s_waitcnt lgkmcnt(0)
	v_lshl_add_u64 v[8:9], s[18:19], 0, v[4:5]
	v_lshl_add_u64 v[8:9], v[8:9], 0, s[10:11]
	s_mov_b64 s[10:11], 0
	v_lshl_add_u64 v[52:53], v[6:7], 0, s[10:11]
	global_load_dwordx4 v[70:73], v[52:53], off
	global_load_dwordx4 v[74:77], v[52:53], off offset:16
	global_load_dwordx4 v[78:81], v[52:53], off offset:32
	global_load_dwordx4 v[82:85], v[52:53], off offset:48
	v_add_co_u32_e32 v54, vcc, s13, v8
	s_add_u32 s10, s10, 64
	s_nop 0
	v_addc_co_u32_e32 v55, vcc, -1, v9, vcc
	v_add_co_u32_e32 v56, vcc, s14, v8
	s_addc_u32 s11, s11, 0
	s_nop 0
	v_addc_co_u32_e32 v57, vcc, -1, v9, vcc
	v_add_co_u32_e32 v58, vcc, s15, v8
	s_nop 1
	v_addc_co_u32_e32 v59, vcc, -1, v9, vcc
	global_load_dword v134, v[54:55], off offset:-3072
	global_load_dword v135, v[54:55], off offset:-2048
	global_load_dword v136, v[54:55], off offset:-1024
	global_load_dword v137, v[56:57], off offset:-4096
	global_load_dword v138, v[56:57], off offset:-3072
	global_load_dword v139, v[56:57], off offset:-2048
	global_load_dword v140, v[56:57], off offset:-1024
	global_load_dword v141, v[56:57], off
	global_load_dword v142, v[58:59], off offset:-3072
	global_load_dword v143, v[58:59], off offset:-2048
	global_load_dword v144, v[58:59], off offset:-1024
	global_load_dword v145, v[8:9], off offset:-4096
	global_load_dword v146, v[8:9], off offset:-3072
	global_load_dword v147, v[8:9], off offset:-2048
	global_load_dword v148, v[8:9], off offset:-1024
	global_load_dword v149, v[8:9], off
	v_lshl_add_u64 v[8:9], v[8:9], 0, s[6:7]
	v_lshl_add_u64 v[52:53], v[6:7], 0, s[10:11]
	global_load_dwordx4 v[86:89], v[52:53], off
	global_load_dwordx4 v[90:93], v[52:53], off offset:16
	global_load_dwordx4 v[94:97], v[52:53], off offset:32
	global_load_dwordx4 v[98:101], v[52:53], off offset:48
	v_add_co_u32_e32 v54, vcc, s13, v8
	s_add_u32 s10, s10, 64
	s_nop 0
	v_addc_co_u32_e32 v55, vcc, -1, v9, vcc
	v_add_co_u32_e32 v56, vcc, s14, v8
	s_addc_u32 s11, s11, 0
	s_nop 0
	v_addc_co_u32_e32 v57, vcc, -1, v9, vcc
	v_add_co_u32_e32 v58, vcc, s15, v8
	s_nop 1
	v_addc_co_u32_e32 v59, vcc, -1, v9, vcc
	global_load_dword v150, v[54:55], off offset:-3072
	global_load_dword v151, v[54:55], off offset:-2048
	global_load_dword v152, v[54:55], off offset:-1024
	global_load_dword v153, v[56:57], off offset:-4096
	global_load_dword v154, v[56:57], off offset:-3072
	global_load_dword v155, v[56:57], off offset:-2048
	global_load_dword v156, v[56:57], off offset:-1024
	global_load_dword v157, v[56:57], off
	global_load_dword v158, v[58:59], off offset:-3072
	global_load_dword v159, v[58:59], off offset:-2048
	global_load_dword v160, v[58:59], off offset:-1024
	global_load_dword v161, v[8:9], off offset:-4096
	global_load_dword v162, v[8:9], off offset:-3072
	global_load_dword v163, v[8:9], off offset:-2048
	global_load_dword v164, v[8:9], off offset:-1024
	global_load_dword v165, v[8:9], off
	v_lshl_add_u64 v[8:9], v[8:9], 0, s[6:7]
	v_lshl_add_u64 v[52:53], v[6:7], 0, s[10:11]
	global_load_dwordx4 v[102:105], v[52:53], off
	global_load_dwordx4 v[106:109], v[52:53], off offset:16
	global_load_dwordx4 v[110:113], v[52:53], off offset:32
	global_load_dwordx4 v[114:117], v[52:53], off offset:48
	v_add_co_u32_e32 v54, vcc, s13, v8
	s_add_u32 s10, s10, 64
	s_nop 0
	v_addc_co_u32_e32 v55, vcc, -1, v9, vcc
	v_add_co_u32_e32 v56, vcc, s14, v8
	s_addc_u32 s11, s11, 0
	s_nop 0
	v_addc_co_u32_e32 v57, vcc, -1, v9, vcc
	v_add_co_u32_e32 v58, vcc, s15, v8
	s_nop 1
	v_addc_co_u32_e32 v59, vcc, -1, v9, vcc
	global_load_dword v166, v[54:55], off offset:-3072
	global_load_dword v167, v[54:55], off offset:-2048
	global_load_dword v168, v[54:55], off offset:-1024
	global_load_dword v169, v[56:57], off offset:-4096
	global_load_dword v170, v[56:57], off offset:-3072
	global_load_dword v171, v[56:57], off offset:-2048
	global_load_dword v172, v[56:57], off offset:-1024
	global_load_dword v173, v[56:57], off
	global_load_dword v174, v[58:59], off offset:-3072
	global_load_dword v175, v[58:59], off offset:-2048
	global_load_dword v176, v[58:59], off offset:-1024
	global_load_dword v177, v[8:9], off offset:-4096
	global_load_dword v178, v[8:9], off offset:-3072
	global_load_dword v179, v[8:9], off offset:-2048
	global_load_dword v180, v[8:9], off offset:-1024
	global_load_dword v181, v[8:9], off
	v_lshl_add_u64 v[8:9], v[8:9], 0, s[6:7]
	s_waitcnt vmcnt(40)
; __global__ void __launch_bounds__(512, 2) fwd_megakernel(Args args) {
;     ...
;             float a = 0.f;
; #pragma unroll 16
;             for (int k = 0; k < 64; ++k) a += pos[k] * w1[(size_t)k * 256];
;             float* part = (float*)lds; part[sl * 16 + col] = a;
;             __syncthreads();
;             if (tid < 16) { float s = 0.f;
; #pragma unroll
;                 for (int s2 = 0; s2 < 32; ++s2) s += part[s2 * 16 + tid];
;                 ((float*)(ws + (size_t)l * LW_BYTES + LW_B1))[isv * 256 + ng * 16 + tid] = s; }
	v_fmac_f32_e32 v12, v70, v134
	v_fmac_f32_e32 v12, v71, v135
	v_fmac_f32_e32 v12, v72, v136
	v_fmac_f32_e32 v12, v73, v137
	v_fmac_f32_e32 v12, v74, v138
	v_fmac_f32_e32 v12, v75, v139
	v_fmac_f32_e32 v12, v76, v140
	v_fmac_f32_e32 v12, v77, v141
	v_fmac_f32_e32 v12, v78, v142
	v_fmac_f32_e32 v12, v79, v143
	v_fmac_f32_e32 v12, v80, v144
	v_fmac_f32_e32 v12, v81, v145
	v_fmac_f32_e32 v12, v82, v146
	v_fmac_f32_e32 v12, v83, v147
	v_fmac_f32_e32 v12, v84, v148
	v_fmac_f32_e32 v12, v85, v149
	v_lshl_add_u64 v[52:53], v[6:7], 0, s[10:11]
	global_load_dwordx4 v[118:121], v[52:53], off
	global_load_dwordx4 v[122:125], v[52:53], off offset:16
	global_load_dwordx4 v[126:129], v[52:53], off offset:32
	global_load_dwordx4 v[130:133], v[52:53], off offset:48
	v_add_co_u32_e32 v54, vcc, s13, v8
	s_add_u32 s10, s10, 64
	s_nop 0
	v_addc_co_u32_e32 v55, vcc, -1, v9, vcc
	v_add_co_u32_e32 v56, vcc, s14, v8
	s_addc_u32 s11, s11, 0
	s_nop 0
	v_addc_co_u32_e32 v57, vcc, -1, v9, vcc
	v_add_co_u32_e32 v58, vcc, s15, v8
	s_nop 1
	v_addc_co_u32_e32 v59, vcc, -1, v9, vcc
	global_load_dword v182, v[54:55], off offset:-3072
	global_load_dword v183, v[54:55], off offset:-2048
	global_load_dword v184, v[54:55], off offset:-1024
	global_load_dword v185, v[56:57], off offset:-4096
	global_load_dword v186, v[56:57], off offset:-3072
	global_load_dword v187, v[56:57], off offset:-2048
	global_load_dword v188, v[56:57], off offset:-1024
	global_load_dword v189, v[56:57], off
	global_load_dword v190, v[58:59], off offset:-3072
	global_load_dword v191, v[58:59], off offset:-2048
	global_load_dword v192, v[58:59], off offset:-1024
	global_load_dword v193, v[8:9], off offset:-4096
	global_load_dword v194, v[8:9], off offset:-3072
	global_load_dword v195, v[8:9], off offset:-2048
	global_load_dword v196, v[8:9], off offset:-1024
	global_load_dword v197, v[8:9], off
	v_lshl_add_u64 v[8:9], v[8:9], 0, s[6:7]
	s_waitcnt vmcnt(40)
	v_fmac_f32_e32 v12, v86, v150
	v_fmac_f32_e32 v12, v87, v151
	v_fmac_f32_e32 v12, v88, v152
	v_fmac_f32_e32 v12, v89, v153
	v_fmac_f32_e32 v12, v90, v154
	v_fmac_f32_e32 v12, v91, v155
	v_fmac_f32_e32 v12, v92, v156
	v_fmac_f32_e32 v12, v93, v157
	v_fmac_f32_e32 v12, v94, v158
	v_fmac_f32_e32 v12, v95, v159
	v_fmac_f32_e32 v12, v96, v160
	v_fmac_f32_e32 v12, v97, v161
	v_fmac_f32_e32 v12, v98, v162
	v_fmac_f32_e32 v12, v99, v163
	v_fmac_f32_e32 v12, v100, v164
	v_fmac_f32_e32 v12, v101, v165
	s_waitcnt vmcnt(20)
	v_fmac_f32_e32 v12, v102, v166
	v_fmac_f32_e32 v12, v103, v167
	v_fmac_f32_e32 v12, v104, v168
	v_fmac_f32_e32 v12, v105, v169
	v_fmac_f32_e32 v12, v106, v170
	v_fmac_f32_e32 v12, v107, v171
	v_fmac_f32_e32 v12, v108, v172
	v_fmac_f32_e32 v12, v109, v173
	v_fmac_f32_e32 v12, v110, v174
	v_fmac_f32_e32 v12, v111, v175
	v_fmac_f32_e32 v12, v112, v176
	v_fmac_f32_e32 v12, v113, v177
	v_fmac_f32_e32 v12, v114, v178
	v_fmac_f32_e32 v12, v115, v179
	v_fmac_f32_e32 v12, v116, v180
	v_fmac_f32_e32 v12, v117, v181
	s_waitcnt vmcnt(0)
	v_fmac_f32_e32 v12, v118, v182
	v_fmac_f32_e32 v12, v119, v183
	v_fmac_f32_e32 v12, v120, v184
	v_fmac_f32_e32 v12, v121, v185
	v_fmac_f32_e32 v12, v122, v186
	v_fmac_f32_e32 v12, v123, v187
	v_fmac_f32_e32 v12, v124, v188
	v_fmac_f32_e32 v12, v125, v189
	v_fmac_f32_e32 v12, v126, v190
	v_fmac_f32_e32 v12, v127, v191
	v_fmac_f32_e32 v12, v128, v192
	v_fmac_f32_e32 v12, v129, v193
	v_fmac_f32_e32 v12, v130, v194
	v_fmac_f32_e32 v12, v131, v195
	v_fmac_f32_e32 v12, v132, v196
	v_fmac_f32_e32 v12, v133, v197
	ds_write_b32 v10, v12
	s_waitcnt lgkmcnt(0)
	s_barrier
	s_and_saveexec_b64 s[10:11], s[4:5]
	s_cbranch_execz .LBB0_192
	ds_read2_b32 v[6:7], v10 offset1:16
	ds_read2_b32 v[8:9], v10 offset0:32 offset1:48
	ds_read2_b32 v[12:13], v10 offset0:64 offset1:80
	s_lshl_b32 s9, s16, 4
	s_and_b32 s18, s9, 0xf0
	s_mul_hi_i32 s9, s8, 0xb65a400
	s_waitcnt lgkmcnt(2)
	v_add_f32_e32 v6, 0, v6
	v_add_f32_e32 v6, v6, v7
	s_waitcnt lgkmcnt(1)
	v_add_f32_e32 v8, v6, v8
	ds_read2_b32 v[6:7], v10 offset0:96 offset1:112
	v_add_f32_e32 v8, v8, v9
	s_waitcnt lgkmcnt(1)
	v_add_f32_e32 v12, v8, v12
	ds_read2_b32 v[8:9], v10 offset0:128 offset1:144
	v_add_f32_e32 v12, v12, v13
	s_waitcnt lgkmcnt(1)
	v_add_f32_e32 v6, v12, v6
	ds_read2_b32 v[12:13], v10 offset0:160 offset1:176
	v_add_f32_e32 v6, v6, v7
	s_waitcnt lgkmcnt(1)
	v_add_f32_e32 v8, v6, v8
	ds_read2_b32 v[6:7], v10 offset0:192 offset1:208
	v_add_f32_e32 v8, v8, v9
	s_waitcnt lgkmcnt(1)
	v_add_f32_e32 v12, v8, v12
	ds_read2_b32 v[8:9], v10 offset0:224 offset1:240
	v_add_f32_e32 v12, v12, v13
	s_waitcnt lgkmcnt(1)
	v_add_f32_e32 v6, v12, v6
	ds_read2_b32 v[12:13], v11 offset1:16
	v_add_f32_e32 v6, v6, v7
	s_waitcnt lgkmcnt(1)
	v_add_f32_e32 v8, v6, v8
	ds_read2_b32 v[6:7], v11 offset0:32 offset1:48
	v_add_f32_e32 v8, v8, v9
	s_waitcnt lgkmcnt(1)
	v_add_f32_e32 v12, v8, v12
	ds_read2_b32 v[8:9], v11 offset0:64 offset1:80
	v_add_f32_e32 v12, v12, v13
	s_waitcnt lgkmcnt(1)
	v_add_f32_e32 v6, v12, v6
	ds_read2_b32 v[12:13], v11 offset0:96 offset1:112
	v_add_f32_e32 v6, v6, v7
	s_waitcnt lgkmcnt(1)
	v_add_f32_e32 v8, v6, v8
	ds_read2_b32 v[6:7], v11 offset0:128 offset1:144
	v_add_f32_e32 v8, v8, v9
	s_waitcnt lgkmcnt(1)
	v_add_f32_e32 v8, v8, v12
	v_add_f32_e32 v12, v8, v13
	ds_read2_b32 v[8:9], v11 offset0:160 offset1:176
	s_waitcnt lgkmcnt(1)
	v_add_f32_e32 v6, v12, v6
	ds_read2_b32 v[12:13], v11 offset0:192 offset1:208
	v_add_f32_e32 v14, v6, v7
	ds_read2_b32 v[6:7], v11 offset0:224 offset1:240
	s_waitcnt lgkmcnt(2)
	v_add_f32_e32 v8, v14, v8
	v_add_f32_e32 v8, v8, v9
	s_mul_i32 s8, s8, 0xb65a400
	s_waitcnt lgkmcnt(1)
	v_add_f32_e32 v8, v8, v12
	s_add_u32 s8, s62, s8
	v_add_f32_e32 v8, v8, v13
	s_addc_u32 s9, s63, s9
	s_lshl_b32 s17, s17, 8
	s_waitcnt lgkmcnt(0)
	v_add_f32_e32 v6, v8, v6
	s_or_b32 s17, s17, s18
	v_add_f32_e32 v8, v6, v7
	v_add_u32_e32 v6, s17, v1
	v_ashrrev_i32_e32 v7, 31, v6
	v_lshl_add_u64 v[6:7], v[6:7], 2, s[8:9]
	v_add_co_u32_e32 v6, vcc, 0xb650000, v6
	s_nop 1
	v_addc_co_u32_e32 v7, vcc, 0, v7, vcc
	global_store_dword v[6:7], v8, off
	s_branch .LBB0_192

; #define LBAR() do { asm volatile("s_waitcnt lgkmcnt(0)" ::: "memory"); __builtin_amdgcn_s_barrier(); asm volatile("" ::: "memory"); } while (0)
; #define AT_LOAD(s_, k_, v_) do { k_ = *(const u32x4*)(kg + (size_t)(s_) * 4096); v_ = *(const u32x4*)(vg + (s_) * 64); } while (0)
; #define AT_STORE(sb_, k_, v_) do { *(u32x4*)((sb_) + kdst) = k_; *(u32x2*)((sb_) + vdst) = (u32x2){v_.x, v_.y}; *(u32x2*)((sb_) + vdst + 16) = (u32x2){v_.z, v_.w}; } while (0)
; template <int MODE> ...
;     ...
;     float mrun = NEGF, lrun = 0.f;
; #pragma unroll
;     for (int dt = 0; dt < 4; ++dt) o[dt] = (f32x4){0.f, 0.f, 0.f, 0.f};
;     const int crow = tid >> 3, cch = tid & 7;
;     const bf16* kg = K + (size_t)crow * 64 + cch * 8;
;     const bf16* vg = VT + (size_t)crow * 2048 + cch * 8;
;     const int kdst = crow * AKP + cch * 16;
;     const int vdst = 9216 + crow * AKP + ((cch >> 2) * 32 + (cch & 1) * 16 + ((cch & 3) >> 1) * 4) * 2;
;     const int koff = qi * AKP + q4 * 16, voff = 9216 + qi * AKP + q4 * 16;
;     unsigned char* sb0 = lds + AL_KV0; unsigned char* sb1 = sb0 + KV_STAGE;
;     ...
;     u32x4 ka, va, kb = {0u, 0u, 0u, 0u}, vb = {0u, 0u, 0u, 0u};
;     AT_LOAD(st_lo, ka, va);
;     if (st_lo + 1 <= st_hi) AT_LOAD(st_lo + 1, kb, vb);
;     AT_STORE(sb0, ka, va);
;     LBAR();
.LBB0_588:
	v_lshlrev_b32_e32 v45, 5, v60
	v_lshlrev_b32_e32 v46, 2, v60
	v_lshlrev_b32_e32 v116, 3, v44
	s_movk_i32 s0, 0x90
	v_and_b32_e32 v44, 64, v0
	v_and_b32_e32 v45, 32, v45
	v_and_b32_e32 v46, 8, v46
	v_mul_lo_u32 v42, v42, s0
	v_or3_b32 v44, v46, v45, v44
	v_add_u32_e32 v43, v42, v0
	v_add_u32_e32 v42, v42, v44
	v_add_u32_e32 v139, 0x2400, v42
	v_add_u32_e32 v42, 0, v42
	v_add_u32_e32 v141, 0, v43
	v_add_u32_e32 v142, 0xc000, v42
	s_waitcnt vmcnt(1)
	ds_write_b128 v141, v[2:5] offset:40960
	s_waitcnt vmcnt(0)
	ds_write2_b64 v142, v[6:7], v[8:9] offset0:128 offset1:130
	v_lshl_add_u32 v44, v59, 4, v61
	s_and_b32 s0, s38, 1
	s_lshl_b32 s1, s33, 18
	s_waitcnt lgkmcnt(0)
	s_barrier
	v_lshl_add_u64 v[42:43], v[108:109], 0, v[0:1]
	s_lshl_b32 s0, s0, 18
	s_and_b32 s1, s1, 0x380000
	v_add_u32_e32 v143, 0, v44
	v_lshl_add_u64 v[110:111], s[62:63], 0, v[42:43]
	v_lshl_add_u64 v[42:43], v[106:107], 0, v[0:1]
	s_lshl_b32 s12, s69, 17
	v_add_u32_e32 v140, 0x2400, v44
	s_or_b32 s38, s1, s0
	v_add_u32_e32 v144, 0xe800, v143
	v_lshl_add_u64 v[112:113], s[62:63], 0, v[42:43]
	v_sub_u32_e32 v145, v58, v138
	s_add_i32 s13, s80, 0xffffff81
	v_mov_b32_e32 v46, v1
	v_mov_b32_e32 v47, v1
	v_mov_b32_e32 v48, v1
	v_mov_b32_e32 v49, v1
	v_mov_b32_e32 v42, v1
	v_mov_b32_e32 v43, v1
	v_mov_b32_e32 v44, v1
	v_mov_b32_e32 v45, v1
	v_mov_b32_e32 v50, v1
	v_mov_b32_e32 v51, v1
	v_mov_b32_e32 v52, v1
	v_mov_b32_e32 v53, v1
	v_mov_b32_e32 v54, v1
	v_mov_b32_e32 v55, v1
	v_mov_b32_e32 v56, v1
	v_mov_b32_e32 v57, v1
	v_mov_b32_e32 v118, 0xf149f2ca
	v_mov_b32_e32 v117, 0
	s_mov_b32 s14, 3
	s_mov_b32 s0, 0
	v_writelane_b32 v255, s0, 60
	v_writelane_b32 v255, s0, 61
	s_branch .LBB0_590

; #define LBAR() do { asm volatile("s_waitcnt lgkmcnt(0)" ::: "memory"); __builtin_amdgcn_s_barrier(); asm volatile("" ::: "memory"); } while (0)
; #define AT_LOAD(s_, k_, v_) do { k_ = *(const u32x4*)(kg + (size_t)(s_) * 4096); v_ = *(const u32x4*)(vg + (s_) * 64); } while (0)
; #define AT_STORE(sb_, k_, v_) do { *(u32x4*)((sb_) + kdst) = k_; *(u32x2*)((sb_) + vdst) = (u32x2){v_.x, v_.y}; *(u32x2*)((sb_) + vdst + 16) = (u32x2){v_.z, v_.w}; } while (0)
; #define AT_COMPUTE(sb_, s_) do { bool sel_ = true; if (MODE == 0) sel_ = (selm >> (s_)) & 1u; \
;         if ((s_) >= my_lo && (MODE == 1 || __ballot(sel_) != 0ull)) attn_step<MODE>(sb_, s_, qf0, qf1, t, p0, sel_, bias, cfar, o, mrun, lrun, koff, voff, q4); } while (0)
; template <int MODE>
; __device__ __forceinline__ void attn_step(const unsigned char* sb, int st, const bf16x8 qf0, const bf16x8 qf1, int t, int p0, bool sel, const float* bias, float cfar, f32x4 (&o)[4], float& mrun, float& lrun,
;                                           int koff, int voff, int q4) {
;     const int key0 = st * 64;
;     f32x4 s[4];
; #pragma unroll
;     for (int kt = 0; kt < 4; ++kt) {
;         const bf16x8 k0 = *(const bf16x8*)(sb + koff + kt * 16 * AKP), k1 = *(const bf16x8*)(sb + koff + kt * 16 * AKP + 64);
;         s[kt] = (f32x4){0.f, 0.f, 0.f, 0.f};
;         s[kt] = __builtin_amdgcn_mfma_f32_16x16x32_bf16(k0, qf0, s[kt], 0, 0, 0); s[kt] = __builtin_amdgcn_mfma_f32_16x16x32_bf16(k1, qf1, s[kt], 0, 0, 0);
;     }
;     const bool far = (p0 - (key0 + 63) >= BIAS_N - 1) && (MODE == 0 || (p0 + 15 - key0 < 512));
;     bf16x8 vfr[4][2];
; #pragma unroll
;     for (int dt = 0; dt < 4; ++dt) { vfr[dt][0] = *(const bf16x8*)(sb + voff + dt * 16 * AKP); vfr[dt][1] = *(const bf16x8*)(sb + voff + dt * 16 * AKP + 64); }
; template <int MODE> ...
;     ...
;     for (int st = st_lo; st <= st_hi; st += 2) {
;         if (st + 2 <= st_hi) AT_LOAD(st + 2, ka, va);
;         AT_COMPUTE(sb0, st);
;         if (st + 1 <= st_hi) AT_STORE(sb1, kb, vb);
;         LBAR();
;         if (st + 1 > st_hi) break;
;         if (st + 3 <= st_hi) AT_LOAD(st + 3, kb, vb);
;         AT_COMPUTE(sb1, st + 1);
.LBB0_592:
	s_add_i32 s16, s14, -3
	s_waitcnt lgkmcnt(2)
	v_bfe_u32 v125, v115, s16, 1
	v_cmp_ne_u32_e32 vcc, 0, v125
	s_cbranch_vccz .Lsel_X_skip
	ds_read_b128 v[180:183], v143 offset:40960
	ds_read_b128 v[184:187], v143 offset:43264
	ds_read_b128 v[188:191], v143 offset:45568
	ds_read_b128 v[192:195], v143 offset:47872
	ds_read_b128 v[196:199], v143 offset:41024
	ds_read_b128 v[220:223], v143 offset:43328
	ds_read_b128 v[240:243], v143 offset:45632
	ds_read_b128 v[244:247], v143 offset:47936
	v_readlane_b32 s10, v255, 60
	s_nop 3
	s_cmp_eq_u32 s10, 0
	s_cbranch_scc1 .Lsel_X_qk
	s_mov_b32 s10, 0
	v_writelane_b32 v255, s10, 61
	s_branch .Lsel_BdY
.Lsel_X_qk:
	s_waitcnt lgkmcnt(7)
	v_mfma_f32_16x16x32_bf16 v[102:105], v[180:183], v[18:21], 0
	ds_read_b128 v[86:89], v143 offset:50176
	s_waitcnt lgkmcnt(7)
	v_mfma_f32_16x16x32_bf16 v[98:101], v[184:187], v[18:21], 0
	ds_read_b128 v[82:85], v143 offset:50240
	s_waitcnt lgkmcnt(7)
	v_mfma_f32_16x16x32_bf16 v[94:97], v[188:191], v[18:21], 0
	ds_read_b128 v[78:81], v143 offset:52480
	s_waitcnt lgkmcnt(7)
	v_mfma_f32_16x16x32_bf16 v[90:93], v[192:195], v[18:21], 0
	ds_read_b128 v[74:77], v143 offset:52544
	s_waitcnt lgkmcnt(7)
	v_mfma_f32_16x16x32_bf16 v[102:105], v[196:199], v[22:25], v[102:105]
	ds_read_b128 v[70:73], v143 offset:54784
	s_waitcnt lgkmcnt(7)
	v_mfma_f32_16x16x32_bf16 v[98:101], v[220:223], v[22:25], v[98:101]
	ds_read_b128 v[66:69], v143 offset:54848
	s_waitcnt lgkmcnt(7)
	v_mfma_f32_16x16x32_bf16 v[94:97], v[240:243], v[22:25], v[94:97]
	ds_read_b128 v[62:65], v143 offset:57088
	s_waitcnt lgkmcnt(7)
	v_mfma_f32_16x16x32_bf16 v[90:93], v[244:247], v[22:25], v[90:93]
	ds_read_b128 v[58:61], v143 offset:57152
	s_mov_b32 s10, 1
	v_writelane_b32 v255, s10, 60
	s_branch .Lsel_X_tail
.Lsel_X_skip:
	v_readlane_b32 s10, v255, 60
	s_nop 3
	s_cmp_eq_u32 s10, 0
	s_cbranch_scc1 .Lsel_X_skip_go
	s_mov_b32 s10, 2
	v_writelane_b32 v255, s10, 61
	s_branch .Lsel_BdY
.Lsel_X_skip_go:
	v_mov_b32_e32 v119, v118
	s_cmp_lt_u32 s16, s97
	s_cselect_b64 s[0:1], -1, 0
	s_cmp_ge_u32 s16, s97
	s_cbranch_scc0 .LBB0_602
	s_branch .LBB0_603
.Lsel_X_tail:
	s_cmp_lt_u32 s16, s97
	s_cselect_b64 s[0:1], -1, 0
	s_cmp_ge_u32 s16, s97
	s_cbranch_scc1 .LBB0_603

; #define AT_LOAD(s_, k_, v_) do { k_ = *(const u32x4*)(kg + (size_t)(s_) * 4096); v_ = *(const u32x4*)(vg + (s_) * 64); } while (0)
; #define AT_COMPUTE(sb_, s_) do { bool sel_ = true; if (MODE == 0) sel_ = (selm >> (s_)) & 1u; \
;         if ((s_) >= my_lo && (MODE == 1 || __ballot(sel_) != 0ull)) attn_step<MODE>(sb_, s_, qf0, qf1, t, p0, sel_, bias, cfar, o, mrun, lrun, koff, voff, q4); } while (0)
; template <int MODE>
; __device__ __forceinline__ void attn_step(const unsigned char* sb, int st, const bf16x8 qf0, const bf16x8 qf1, int t, int p0, bool sel, const float* bias, float cfar, f32x4 (&o)[4], float& mrun, float& lrun,
;                                           int koff, int voff, int q4) {
;     const int key0 = st * 64;
;     f32x4 s[4];
; #pragma unroll
;     for (int kt = 0; kt < 4; ++kt) {
;         const bf16x8 k0 = *(const bf16x8*)(sb + koff + kt * 16 * AKP), k1 = *(const bf16x8*)(sb + koff + kt * 16 * AKP + 64);
;         s[kt] = (f32x4){0.f, 0.f, 0.f, 0.f};
;         s[kt] = __builtin_amdgcn_mfma_f32_16x16x32_bf16(k0, qf0, s[kt], 0, 0, 0); s[kt] = __builtin_amdgcn_mfma_f32_16x16x32_bf16(k1, qf1, s[kt], 0, 0, 0);
;     }
;     const bool far = (p0 - (key0 + 63) >= BIAS_N - 1) && (MODE == 0 || (p0 + 15 - key0 < 512));
;     bf16x8 vfr[4][2];
; #pragma unroll
;     for (int dt = 0; dt < 4; ++dt) { vfr[dt][0] = *(const bf16x8*)(sb + voff + dt * 16 * AKP); vfr[dt][1] = *(const bf16x8*)(sb + voff + dt * 16 * AKP + 64); }
; template <int MODE> ...
;     ...
;         if (st + 3 <= st_hi) AT_LOAD(st + 3, kb, vb);
;         AT_COMPUTE(sb1, st + 1);
.LBB0_606:
	s_add_i32 s10, s14, -2
	v_bfe_u32 v125, v115, s10, 1
	v_cmp_ne_u32_e32 vcc, 0, v125
	s_cbranch_vccz .Lsel_Y_skip
	ds_read_b128 v[180:183], v143 offset:59392
	ds_read_b128 v[184:187], v143 offset:61696
	ds_read_b128 v[188:191], v143 offset:64000
	ds_read_b128 v[192:195], v144 offset:6912
	ds_read_b128 v[196:199], v143 offset:59456
	ds_read_b128 v[220:223], v143 offset:61760
	ds_read_b128 v[240:243], v143 offset:64064
	ds_read_b128 v[244:247], v144 offset:6976
	v_readlane_b32 s10, v255, 60
	s_nop 3
	s_cmp_eq_u32 s10, 0
	s_cbranch_scc1 .Lsel_Y_qk
	s_mov_b32 s10, 0
	v_writelane_b32 v255, s10, 61
	s_branch .Lsel_BdX
.Lsel_Y_qk:
	s_add_i32 s10, 0, 0xe800
	s_waitcnt lgkmcnt(7)
	v_mfma_f32_16x16x32_bf16 v[102:105], v[180:183], v[18:21], 0
	v_add_u32_e32 v58, 0, v140
	ds_read_b128 v[86:89], v58 offset:59392
	s_waitcnt lgkmcnt(7)
	v_mfma_f32_16x16x32_bf16 v[98:101], v[184:187], v[18:21], 0
	ds_read_b128 v[82:85], v58 offset:59456
	s_waitcnt lgkmcnt(7)
	v_mfma_f32_16x16x32_bf16 v[94:97], v[188:191], v[18:21], 0
	ds_read_b128 v[78:81], v58 offset:61696
	s_waitcnt lgkmcnt(7)
	v_mfma_f32_16x16x32_bf16 v[90:93], v[192:195], v[18:21], 0
	ds_read_b128 v[74:77], v58 offset:61760
	s_waitcnt lgkmcnt(7)
	v_mfma_f32_16x16x32_bf16 v[102:105], v[196:199], v[22:25], v[102:105]
	ds_read_b128 v[70:73], v58 offset:64000
	s_waitcnt lgkmcnt(7)
	v_mfma_f32_16x16x32_bf16 v[98:101], v[220:223], v[22:25], v[98:101]
	ds_read_b128 v[66:69], v58 offset:64064
	s_waitcnt lgkmcnt(7)
	v_mfma_f32_16x16x32_bf16 v[94:97], v[240:243], v[22:25], v[94:97]
	v_add_u32_e32 v58, s10, v140
	ds_read_b128 v[62:65], v58 offset:6912
	s_waitcnt lgkmcnt(7)
	v_mfma_f32_16x16x32_bf16 v[90:93], v[244:247], v[22:25], v[90:93]
	ds_read_b128 v[58:61], v58 offset:6976
	s_mov_b32 s10, 2
	v_writelane_b32 v255, s10, 60
	s_branch .Lsel_Y_tail

; #define AT_LOAD(s_, k_, v_) do { k_ = *(const u32x4*)(kg + (size_t)(s_) * 4096); v_ = *(const u32x4*)(vg + (s_) * 64); } while (0)
; #define AT_STORE(sb_, k_, v_) do { *(u32x4*)((sb_) + kdst) = k_; *(u32x2*)((sb_) + vdst) = (u32x2){v_.x, v_.y}; *(u32x2*)((sb_) + vdst + 16) = (u32x2){v_.z, v_.w}; } while (0)
; #define AT_COMPUTE(sb_, s_) do { bool sel_ = true; if (MODE == 0) sel_ = (selm >> (s_)) & 1u; \
;         if ((s_) >= my_lo && (MODE == 1 || __ballot(sel_) != 0ull)) attn_step<MODE>(sb_, s_, qf0, qf1, t, p0, sel_, bias, cfar, o, mrun, lrun, koff, voff, q4); } while (0)
; template <int MODE> ...
;     ...
;         if (st + 1 > st_hi) break;
;         if (st + 3 <= st_hi) AT_LOAD(st + 3, kb, vb);
;         AT_COMPUTE(sb1, st + 1);
;         if (st + 2 <= st_hi) AT_STORE(sb0, ka, va);
.Lsel_Y_skip_go:
	v_mov_b32_e32 v118, v119
	s_andn2_b64 vcc, exec, s[6:7]
	s_cbranch_vccnz .LBB0_589
	s_branch .LBB0_617
.Lsel_Y_tail:
	s_andn2_b64 vcc, exec, s[6:7]
	s_cbranch_vccnz .LBB0_589

; template <int MODE>
; __device__ __forceinline__ void attn_step(const unsigned char* sb, int st, const bf16x8 qf0, const bf16x8 qf1, int t, int p0, bool sel, const float* bias, float cfar, f32x4 (&o)[4], float& mrun, float& lrun,
;                                           int koff, int voff, int q4) {
;     ...
;     const bool far = (p0 - (key0 + 63) >= BIAS_N - 1) && (MODE == 0 || (p0 + 15 - key0 < 512));
;     bf16x8 vfr[4][2];
; #pragma unroll
;     for (int dt = 0; dt < 4; ++dt) { vfr[dt][0] = *(const bf16x8*)(sb + voff + dt * 16 * AKP); vfr[dt][1] = *(const bf16x8*)(sb + voff + dt * 16 * AKP + 64); }
;     float fsc = 1.f, fc = 0.f;
;     if (far) {
;         fc = (MODE == 0 && !sel) ? MASKV : cfar; fsc = (MODE == 0 && !sel) ? 0.f : SC2;
;     } else {
; #pragma unroll
;         for (int kt = 0; kt < 4; ++kt)
; #pragma unroll
;             for (int j = 0; j < 4; ++j) {
;                 const int dist = t - (key0 + kt * 16 + q4 * 4 + j);
;                 const bool v = (dist >= 0) && (MODE == 0 ? sel : (dist < 512));
;                 const int bi = dist < 0 ? 0 : (dist > BIAS_N - 1 ? BIAS_N - 1 : dist);
;                 const float l = s[kt][j] * SC2 + bias[bi];
;                 s[kt][j] = v ? l : MASKV;
;             }
;     }
.Lsel_yt_nold:
	s_waitcnt vmcnt(1)
	ds_write_b128 v141, v[2:5] offset:40960
	s_waitcnt vmcnt(0)
	ds_write2_b64 v142, v[6:7], v[8:9] offset0:128 offset1:130
	s_branch .LBB0_589
.LBB0_610:
	s_and_b64 vcc, exec, s[0:1]
	s_cbranch_vccz .LBB0_590
	s_branch .LBB0_618
.Lsel_BdX:
	s_add_i32 s10, s14, -3
	v_bfe_u32 v125, v115, s10, 1
	v_cmp_ne_u32_e64 s[0:1], 0, v125
	s_add_i32 s10, s13, 64
	s_cmpk_gt_i32 s10, 0x70
	s_cbranch_scc1 .Lsel_BdX_far
	v_add_u32_e32 v114, s13, v145
	v_add_u32_e32 v179, 0x7f, v114
	v_add_u32_e32 v200, 0x7e, v114
	v_add_u32_e32 v201, 0x7d, v114
	v_add_u32_e32 v216, 0x7c, v114
	v_add_u32_e32 v218, 0x6f, v114
	v_add_u32_e32 v219, 0x6e, v114
	v_add_u32_e32 v224, 0x6d, v114
	v_add_u32_e32 v225, 0x6c, v114
	v_add_u32_e32 v234, 0x5f, v114
	v_add_u32_e32 v235, 0x5e, v114
	v_add_u32_e32 v238, 0x5d, v114
	v_add_u32_e32 v239, 0x5c, v114
	v_add_u32_e32 v248, 0x4f, v114
	v_add_u32_e32 v249, 0x4e, v114
	v_add_u32_e32 v250, 0x4d, v114
	v_add_u32_e32 v251, 0x4c, v114
	v_med3_i32 v179, v179, 0, v227
	v_med3_i32 v200, v200, 0, v227
	v_med3_i32 v201, v201, 0, v227
	v_med3_i32 v216, v216, 0, v227
	v_med3_i32 v218, v218, 0, v227
	v_med3_i32 v219, v219, 0, v227
	v_med3_i32 v224, v224, 0, v227
	v_med3_i32 v225, v225, 0, v227
	v_med3_i32 v234, v234, 0, v227
	v_med3_i32 v235, v235, 0, v227
	v_med3_i32 v238, v238, 0, v227
	v_med3_i32 v239, v239, 0, v227
	v_med3_i32 v248, v248, 0, v227
	v_med3_i32 v249, v249, 0, v227
	v_med3_i32 v250, v250, 0, v227
	v_med3_i32 v251, v251, 0, v227
	v_lshl_add_u32 v179, v179, 2, s85
	v_lshl_add_u32 v200, v200, 2, s85
	v_lshl_add_u32 v201, v201, 2, s85
	v_lshl_add_u32 v216, v216, 2, s85
	v_lshl_add_u32 v218, v218, 2, s85
	v_lshl_add_u32 v219, v219, 2, s85
	v_lshl_add_u32 v224, v224, 2, s85
	v_lshl_add_u32 v225, v225, 2, s85
	v_lshl_add_u32 v234, v234, 2, s85
	v_lshl_add_u32 v235, v235, 2, s85
	v_lshl_add_u32 v238, v238, 2, s85
	v_lshl_add_u32 v239, v239, 2, s85
	v_lshl_add_u32 v248, v248, 2, s85
	v_lshl_add_u32 v249, v249, 2, s85
	v_lshl_add_u32 v250, v250, 2, s85
	v_lshl_add_u32 v251, v251, 2, s85
	ds_read_b32 v179, v179
	ds_read_b32 v200, v200
	ds_read_b32 v201, v201
	ds_read_b32 v216, v216
	ds_read_b32 v218, v218
	ds_read_b32 v219, v219
	ds_read_b32 v224, v224
	ds_read_b32 v225, v225
	ds_read_b32 v234, v234
	ds_read_b32 v235, v235
	ds_read_b32 v238, v238
	ds_read_b32 v239, v239
	ds_read_b32 v248, v248
	ds_read_b32 v249, v249
	ds_read_b32 v250, v250
	ds_read_b32 v251, v251
	s_waitcnt lgkmcnt(12)
	v_cmp_lt_i32_e32 vcc, 0xffffff80, v114
	s_and_b64 vcc, s[0:1], vcc
	v_fmac_f32_e32 v179, 0x3e38aa3b, v102
	v_cndmask_b32_e32 v102, v228, v179, vcc
	v_cmp_lt_i32_e32 vcc, 0xffffff81, v114
	s_and_b64 vcc, s[0:1], vcc
	v_fmac_f32_e32 v200, 0x3e38aa3b, v103
	v_cndmask_b32_e32 v103, v228, v200, vcc
	v_cmp_lt_i32_e32 vcc, 0xffffff82, v114
	s_and_b64 vcc, s[0:1], vcc
	v_fmac_f32_e32 v201, 0x3e38aa3b, v104
	v_cndmask_b32_e32 v104, v228, v201, vcc
	v_cmp_lt_i32_e32 vcc, 0xffffff83, v114
	s_and_b64 vcc, s[0:1], vcc
	v_fmac_f32_e32 v216, 0x3e38aa3b, v105
	v_cndmask_b32_e32 v105, v228, v216, vcc
	s_waitcnt lgkmcnt(8)
	v_cmp_lt_i32_e32 vcc, 0xffffff90, v114
	s_and_b64 vcc, s[0:1], vcc
	v_fmac_f32_e32 v218, 0x3e38aa3b, v98
	v_cndmask_b32_e32 v98, v228, v218, vcc
	v_cmp_lt_i32_e32 vcc, 0xffffff91, v114
	s_and_b64 vcc, s[0:1], vcc
	v_fmac_f32_e32 v219, 0x3e38aa3b, v99
	v_cndmask_b32_e32 v99, v228, v219, vcc
	v_cmp_lt_i32_e32 vcc, 0xffffff92, v114
	s_and_b64 vcc, s[0:1], vcc
	v_fmac_f32_e32 v224, 0x3e38aa3b, v100
	v_cndmask_b32_e32 v100, v228, v224, vcc
	v_cmp_lt_i32_e32 vcc, 0xffffff93, v114
	s_and_b64 vcc, s[0:1], vcc
	v_fmac_f32_e32 v225, 0x3e38aa3b, v101
	v_cndmask_b32_e32 v101, v228, v225, vcc
	s_waitcnt lgkmcnt(4)
	v_cmp_lt_i32_e32 vcc, 0xffffffa0, v114
	s_and_b64 vcc, s[0:1], vcc
	v_fmac_f32_e32 v234, 0x3e38aa3b, v94
	v_cndmask_b32_e32 v94, v228, v234, vcc
	v_cmp_lt_i32_e32 vcc, 0xffffffa1, v114
	s_and_b64 vcc, s[0:1], vcc
	v_fmac_f32_e32 v235, 0x3e38aa3b, v95
	v_cndmask_b32_e32 v95, v228, v235, vcc
	v_cmp_lt_i32_e32 vcc, 0xffffffa2, v114
	s_and_b64 vcc, s[0:1], vcc
	v_fmac_f32_e32 v238, 0x3e38aa3b, v96
	v_cndmask_b32_e32 v96, v228, v238, vcc
	v_cmp_lt_i32_e32 vcc, 0xffffffa3, v114
	s_and_b64 vcc, s[0:1], vcc
	v_fmac_f32_e32 v239, 0x3e38aa3b, v97
	v_cndmask_b32_e32 v97, v228, v239, vcc
	s_waitcnt lgkmcnt(0)
	v_cmp_lt_i32_e32 vcc, 0xffffffb0, v114
	s_and_b64 vcc, s[0:1], vcc
	v_fmac_f32_e32 v248, 0x3e38aa3b, v90
	v_cndmask_b32_e32 v90, v228, v248, vcc
	v_cmp_lt_i32_e32 vcc, 0xffffffb1, v114
	s_and_b64 vcc, s[0:1], vcc
	v_fmac_f32_e32 v249, 0x3e38aa3b, v91
	v_cndmask_b32_e32 v91, v228, v249, vcc
	v_cmp_lt_i32_e32 vcc, 0xffffffb2, v114
	s_and_b64 vcc, s[0:1], vcc
	v_fmac_f32_e32 v250, 0x3e38aa3b, v92
	v_cndmask_b32_e32 v92, v228, v250, vcc
	v_cmp_lt_i32_e32 vcc, 0xffffffb3, v114
	s_and_b64 vcc, s[0:1], vcc
	v_fmac_f32_e32 v251, 0x3e38aa3b, v93
	v_cndmask_b32_e32 v93, v228, v251, vcc
	v_mov_b32_e32 v114, 1.0
	v_mov_b32_e32 v121, 0
	s_branch .Lsel_BdX_common

; __device__ __forceinline__ bf16x8 pack_p(const float* a, const float* b) { u32x4 w; w.x = cvtpk(a[0], a[1]); w.y = cvtpk(a[2], a[3]); w.z = cvtpk(b[0], b[1]); w.w = cvtpk(b[2], b[3]); return __builtin_bit_cast(bf16x8, w); }
; template <int MODE>
; __device__ __forceinline__ void attn_step(const unsigned char* sb, int st, const bf16x8 qf0, const bf16x8 qf1, int t, int p0, bool sel, const float* bias, float cfar, f32x4 (&o)[4], float& mrun, float& lrun,
;                                           int koff, int voff, int q4) {
;     ...
;     f32x4 ps4 = {0.f, 0.f, 0.f, 0.f};
;     const float foff = fc - mnew;
; #pragma unroll
;     for (int kt = 0; kt < 4; ++kt) {
;         s[kt] = s[kt] * fsc + foff;
; #pragma unroll
;         for (int j = 0; j < 4; ++j) s[kt][j] = __builtin_amdgcn_exp2f(s[kt][j]);
;         ps4 += s[kt];
;     }
;     const float ps = (ps4.x + ps4.y) + (ps4.z + ps4.w);
;     if (__ballot(mnew != mrun) != 0ull) {
;         const float alpha = __builtin_amdgcn_exp2f(mrun - mnew);
;         lrun *= alpha;
; #pragma unroll
;         for (int dt = 0; dt < 4; ++dt) o[dt] *= alpha;
;     }
;     lrun += ps; mrun = mnew;
;     float pa[4][4];
; #pragma unroll
;     for (int kt = 0; kt < 4; ++kt)
; #pragma unroll
;         for (int j = 0; j < 4; ++j) pa[kt][j] = s[kt][j];
;     const bf16x8 pf0 = pack_p(pa[0], pa[1]), pf1 = pack_p(pa[2], pa[3]);
; #pragma unroll
;     for (int dt = 0; dt < 4; ++dt) {
;         o[dt] = __builtin_amdgcn_mfma_f32_16x16x32_bf16(vfr[dt][0], pf0, o[dt], 0, 0, 0); o[dt] = __builtin_amdgcn_mfma_f32_16x16x32_bf16(vfr[dt][1], pf1, o[dt], 0, 0, 0);
;     }
.Lsel_BdX_resc:
	v_sub_f32_e32 v118, v121, v119
	v_pk_fma_f32 v[104:105], v[104:105], v[114:115], v[118:119] op_sel_hi:[1,0,0]
	v_pk_fma_f32 v[102:103], v[102:103], v[114:115], v[118:119] op_sel_hi:[1,0,0]
	v_exp_f32_e32 v104, v104
	v_exp_f32_e32 v102, v102
	v_exp_f32_e32 v103, v103
	v_exp_f32_e32 v105, v105
	v_pk_fma_f32 v[100:101], v[100:101], v[114:115], v[118:119] op_sel_hi:[1,0,0]
	v_pk_fma_f32 v[98:99], v[98:99], v[114:115], v[118:119] op_sel_hi:[1,0,0]
	v_exp_f32_e32 v100, v100
	v_exp_f32_e32 v98, v98
	v_exp_f32_e32 v99, v99
	v_exp_f32_e32 v101, v101
	v_pk_fma_f32 v[96:97], v[96:97], v[114:115], v[118:119] op_sel_hi:[1,0,0]
	v_pk_fma_f32 v[94:95], v[94:95], v[114:115], v[118:119] op_sel_hi:[1,0,0]
	v_exp_f32_e32 v96, v96
	v_exp_f32_e32 v94, v94
	v_exp_f32_e32 v95, v95
	v_exp_f32_e32 v97, v97
	v_pk_fma_f32 v[92:93], v[92:93], v[114:115], v[118:119] op_sel_hi:[1,0,0]
	v_pk_fma_f32 v[90:91], v[90:91], v[114:115], v[118:119] op_sel_hi:[1,0,0]
	v_exp_f32_e32 v148, v92
	v_exp_f32_e32 v146, v90
	v_exp_f32_e32 v147, v91
	v_exp_f32_e32 v149, v93
	v_pk_add_f32 v[132:133], v[102:103], 0 op_sel_hi:[1,0]
	v_pk_add_f32 v[134:135], v[104:105], 0 op_sel_hi:[1,0]
	v_pk_add_f32 v[132:133], v[98:99], v[132:133]
	v_pk_add_f32 v[134:135], v[100:101], v[134:135]
	v_pk_add_f32 v[132:133], v[94:95], v[132:133]
	v_pk_add_f32 v[134:135], v[96:97], v[134:135]
	v_pk_add_f32 v[92:93], v[146:147], v[132:133]
	v_pk_add_f32 v[90:91], v[148:149], v[134:135]
	v_cvt_pk_bf16_f32 v94, v94, v95
	v_pk_mov_b32 v[132:133], v[92:93], v[90:91] op_sel:[1,0]
	v_mov_b32_e32 v93, v91
	v_pk_add_f32 v[90:91], v[132:133], v[92:93]
	v_cvt_pk_bf16_f32 v92, v98, v99
	v_add_f32_e32 v90, v90, v91
	v_add_f32_e32 v117, v90, v117
	v_cvt_pk_bf16_f32 v90, v102, v103
	v_cvt_pk_bf16_f32 v91, v104, v105
	v_cvt_pk_bf16_f32 v93, v100, v101
	v_cvt_pk_bf16_f32 v95, v96, v97
	v_cvt_pk_bf16_f32 v96, v146, v147
	s_waitcnt lgkmcnt(0)
	v_mfma_f32_16x16x32_bf16 v[46:49], v[86:89], v[90:93], v[46:49]
	v_cvt_pk_bf16_f32 v97, v148, v149
	v_mfma_f32_16x16x32_bf16 v[42:45], v[78:81], v[90:93], v[42:45]
	v_mfma_f32_16x16x32_bf16 v[50:53], v[70:73], v[90:93], v[50:53]
	v_mfma_f32_16x16x32_bf16 v[54:57], v[62:65], v[90:93], v[54:57]
	v_mfma_f32_16x16x32_bf16 v[46:49], v[82:85], v[94:97], v[46:49]
	v_mfma_f32_16x16x32_bf16 v[42:45], v[74:77], v[94:97], v[42:45]
	v_mfma_f32_16x16x32_bf16 v[50:53], v[66:69], v[94:97], v[50:53]
	v_mfma_f32_16x16x32_bf16 v[54:57], v[58:61], v[94:97], v[54:57]
	s_mov_b32 s10, 0
	v_writelane_b32 v255, s10, 60
	s_nop 1
	v_readlane_b32 s10, v255, 61
	s_nop 3
	s_cmp_eq_u32 s10, 0
	s_cbranch_scc1 .Lsel_Y_qk
	s_cmp_eq_u32 s10, 2
	s_cbranch_scc1 .Lsel_Y_skip_go
	s_branch .Lsel_exit_go
; template <int MODE>
; __device__ __forceinline__ void attn_step(const unsigned char* sb, int st, const bf16x8 qf0, const bf16x8 qf1, int t, int p0, bool sel, const float* bias, float cfar, f32x4 (&o)[4], float& mrun, float& lrun,
;                                           int koff, int voff, int q4) {
;     ...
;     if (far) {
;         fc = (MODE == 0 && !sel) ? MASKV : cfar; fsc = (MODE == 0 && !sel) ? 0.f : SC2;
;     } else {
; #pragma unroll
;         for (int kt = 0; kt < 4; ++kt)
; #pragma unroll
;             for (int j = 0; j < 4; ++j) {
;                 const int dist = t - (key0 + kt * 16 + q4 * 4 + j);
;                 const bool v = (dist >= 0) && (MODE == 0 ? sel : (dist < 512));
;                 const int bi = dist < 0 ? 0 : (dist > BIAS_N - 1 ? BIAS_N - 1 : dist);
;                 const float l = s[kt][j] * SC2 + bias[bi];
;                 s[kt][j] = v ? l : MASKV;
;             }
;     }
.Lsel_BdY:
	s_add_i32 s10, s14, -4
	v_bfe_u32 v125, v115, s10, 1
	v_cmp_ne_u32_e64 s[0:1], 0, v125
	s_add_i32 s10, s13, 128
	s_cmpk_gt_i32 s10, 0x70
	s_cbranch_scc1 .Lsel_BdY_far
	v_add_u32_e32 v114, s10, v145
	v_add_u32_e32 v179, 63, v114
	v_add_u32_e32 v200, 62, v114
	v_add_u32_e32 v201, 61, v114
	v_add_u32_e32 v216, 60, v114
	v_add_u32_e32 v218, 47, v114
	v_add_u32_e32 v219, 46, v114
	v_add_u32_e32 v224, 45, v114
	v_add_u32_e32 v225, 44, v114
	v_add_u32_e32 v234, 31, v114
	v_add_u32_e32 v235, 30, v114
	v_add_u32_e32 v238, 29, v114
	v_add_u32_e32 v239, 28, v114
	v_add_u32_e32 v248, 15, v114
	v_add_u32_e32 v249, 14, v114
	v_add_u32_e32 v250, 13, v114
	v_add_u32_e32 v251, 12, v114
	v_med3_i32 v179, v179, 0, v227
	v_med3_i32 v200, v200, 0, v227
	v_med3_i32 v201, v201, 0, v227
	v_med3_i32 v216, v216, 0, v227
	v_med3_i32 v218, v218, 0, v227
	v_med3_i32 v219, v219, 0, v227
	v_med3_i32 v224, v224, 0, v227
	v_med3_i32 v225, v225, 0, v227
	v_med3_i32 v234, v234, 0, v227
	v_med3_i32 v235, v235, 0, v227
	v_med3_i32 v238, v238, 0, v227
	v_med3_i32 v239, v239, 0, v227
	v_med3_i32 v248, v248, 0, v227
	v_med3_i32 v249, v249, 0, v227
	v_med3_i32 v250, v250, 0, v227
	v_med3_i32 v251, v251, 0, v227
	v_lshl_add_u32 v179, v179, 2, s85
	v_lshl_add_u32 v200, v200, 2, s85
	v_lshl_add_u32 v201, v201, 2, s85
	v_lshl_add_u32 v216, v216, 2, s85
	v_lshl_add_u32 v218, v218, 2, s85
	v_lshl_add_u32 v219, v219, 2, s85
	v_lshl_add_u32 v224, v224, 2, s85
	v_lshl_add_u32 v225, v225, 2, s85
	v_lshl_add_u32 v234, v234, 2, s85
	v_lshl_add_u32 v235, v235, 2, s85
	v_lshl_add_u32 v238, v238, 2, s85
	v_lshl_add_u32 v239, v239, 2, s85
	v_lshl_add_u32 v248, v248, 2, s85
	v_lshl_add_u32 v249, v249, 2, s85
	v_lshl_add_u32 v250, v250, 2, s85
	v_lshl_add_u32 v251, v251, 2, s85
	ds_read_b32 v179, v179
	ds_read_b32 v200, v200
	ds_read_b32 v201, v201
	ds_read_b32 v216, v216
	ds_read_b32 v218, v218
	ds_read_b32 v219, v219
	ds_read_b32 v224, v224
	ds_read_b32 v225, v225
	ds_read_b32 v234, v234
	ds_read_b32 v235, v235
	ds_read_b32 v238, v238
	ds_read_b32 v239, v239
	ds_read_b32 v248, v248
	ds_read_b32 v249, v249
	ds_read_b32 v250, v250
	ds_read_b32 v251, v251
	s_waitcnt lgkmcnt(12)
	v_cmp_lt_i32_e32 vcc, 0xffffffc0, v114
	s_and_b64 vcc, s[0:1], vcc
	v_fmac_f32_e32 v179, 0x3e38aa3b, v102
	v_cndmask_b32_e32 v102, v228, v179, vcc
	v_cmp_lt_i32_e32 vcc, 0xffffffc1, v114
	s_and_b64 vcc, s[0:1], vcc
	v_fmac_f32_e32 v200, 0x3e38aa3b, v103
	v_cndmask_b32_e32 v103, v228, v200, vcc
	v_cmp_lt_i32_e32 vcc, 0xffffffc2, v114
	s_and_b64 vcc, s[0:1], vcc
	v_fmac_f32_e32 v201, 0x3e38aa3b, v104
	v_cndmask_b32_e32 v104, v228, v201, vcc
	v_cmp_lt_i32_e32 vcc, 0xffffffc3, v114
	s_and_b64 vcc, s[0:1], vcc
	v_fmac_f32_e32 v216, 0x3e38aa3b, v105
	v_cndmask_b32_e32 v105, v228, v216, vcc
	s_waitcnt lgkmcnt(8)
	v_cmp_lt_i32_e32 vcc, 0xffffffd0, v114
	s_and_b64 vcc, s[0:1], vcc
	v_fmac_f32_e32 v218, 0x3e38aa3b, v98
	v_cndmask_b32_e32 v98, v228, v218, vcc
	v_cmp_lt_i32_e32 vcc, 0xffffffd1, v114
	s_and_b64 vcc, s[0:1], vcc
	v_fmac_f32_e32 v219, 0x3e38aa3b, v99
	v_cndmask_b32_e32 v99, v228, v219, vcc
	v_cmp_lt_i32_e32 vcc, 0xffffffd2, v114
	s_and_b64 vcc, s[0:1], vcc
	v_fmac_f32_e32 v224, 0x3e38aa3b, v100
	v_cndmask_b32_e32 v100, v228, v224, vcc
	v_cmp_lt_i32_e32 vcc, 0xffffffd3, v114
	s_and_b64 vcc, s[0:1], vcc
	v_fmac_f32_e32 v225, 0x3e38aa3b, v101
	v_cndmask_b32_e32 v101, v228, v225, vcc
	s_waitcnt lgkmcnt(4)
	v_cmp_lt_i32_e32 vcc, 0xffffffe0, v114
	s_and_b64 vcc, s[0:1], vcc
	v_fmac_f32_e32 v234, 0x3e38aa3b, v94
	v_cndmask_b32_e32 v94, v228, v234, vcc
	v_cmp_lt_i32_e32 vcc, 0xffffffe1, v114
	s_and_b64 vcc, s[0:1], vcc
	v_fmac_f32_e32 v235, 0x3e38aa3b, v95
	v_cndmask_b32_e32 v95, v228, v235, vcc
	v_cmp_lt_i32_e32 vcc, 0xffffffe2, v114
	s_and_b64 vcc, s[0:1], vcc
	v_fmac_f32_e32 v238, 0x3e38aa3b, v96
	v_cndmask_b32_e32 v96, v228, v238, vcc
	v_cmp_lt_i32_e32 vcc, 0xffffffe3, v114
	s_and_b64 vcc, s[0:1], vcc
	v_fmac_f32_e32 v239, 0x3e38aa3b, v97
	v_cndmask_b32_e32 v97, v228, v239, vcc
	s_waitcnt lgkmcnt(0)
	v_cmp_lt_i32_e32 vcc, 0xfffffff0, v114
	s_and_b64 vcc, s[0:1], vcc
	v_fmac_f32_e32 v248, 0x3e38aa3b, v90
	v_cndmask_b32_e32 v90, v228, v248, vcc
	v_cmp_lt_i32_e32 vcc, 0xfffffff1, v114
	s_and_b64 vcc, s[0:1], vcc
	v_fmac_f32_e32 v249, 0x3e38aa3b, v91
	v_cndmask_b32_e32 v91, v228, v249, vcc
	v_cmp_lt_i32_e32 vcc, 0xfffffff2, v114
	s_and_b64 vcc, s[0:1], vcc
	v_fmac_f32_e32 v250, 0x3e38aa3b, v92
	v_cndmask_b32_e32 v92, v228, v250, vcc
	v_cmp_lt_i32_e32 vcc, 0xfffffff3, v114
	s_and_b64 vcc, s[0:1], vcc
	v_fmac_f32_e32 v251, 0x3e38aa3b, v93
	v_cndmask_b32_e32 v93, v228, v251, vcc
	v_mov_b32_e32 v114, 1.0
	v_mov_b32_e32 v120, 0
	s_branch .Lsel_BdY_common

; __device__ __forceinline__ bf16x8 pack_p(const float* a, const float* b) { u32x4 w; w.x = cvtpk(a[0], a[1]); w.y = cvtpk(a[2], a[3]); w.z = cvtpk(b[0], b[1]); w.w = cvtpk(b[2], b[3]); return __builtin_bit_cast(bf16x8, w); }
; #define LBAR() do { asm volatile("s_waitcnt lgkmcnt(0)" ::: "memory"); __builtin_amdgcn_s_barrier(); asm volatile("" ::: "memory"); } while (0)
; #define AT_LOAD(s_, k_, v_) do { k_ = *(const u32x4*)(kg + (size_t)(s_) * 4096); v_ = *(const u32x4*)(vg + (s_) * 64); } while (0)
; template <int MODE>
; __device__ __forceinline__ void attn_step(const unsigned char* sb, int st, const bf16x8 qf0, const bf16x8 qf1, int t, int p0, bool sel, const float* bias, float cfar, f32x4 (&o)[4], float& mrun, float& lrun,
;                                           int koff, int voff, int q4) {
;     ...
;     f32x4 ps4 = {0.f, 0.f, 0.f, 0.f};
;     const float foff = fc - mnew;
; #pragma unroll
;     for (int kt = 0; kt < 4; ++kt) {
;         s[kt] = s[kt] * fsc + foff;
; #pragma unroll
;         for (int j = 0; j < 4; ++j) s[kt][j] = __builtin_amdgcn_exp2f(s[kt][j]);
;         ps4 += s[kt];
;     }
;     const float ps = (ps4.x + ps4.y) + (ps4.z + ps4.w);
;     if (__ballot(mnew != mrun) != 0ull) {
;         const float alpha = __builtin_amdgcn_exp2f(mrun - mnew);
;         lrun *= alpha;
; #pragma unroll
;         for (int dt = 0; dt < 4; ++dt) o[dt] *= alpha;
;     }
;     lrun += ps; mrun = mnew;
;     float pa[4][4];
; #pragma unroll
;     for (int kt = 0; kt < 4; ++kt)
; #pragma unroll
;         for (int j = 0; j < 4; ++j) pa[kt][j] = s[kt][j];
;     const bf16x8 pf0 = pack_p(pa[0], pa[1]), pf1 = pack_p(pa[2], pa[3]);
; #pragma unroll
;     for (int dt = 0; dt < 4; ++dt) {
;         o[dt] = __builtin_amdgcn_mfma_f32_16x16x32_bf16(vfr[dt][0], pf0, o[dt], 0, 0, 0); o[dt] = __builtin_amdgcn_mfma_f32_16x16x32_bf16(vfr[dt][1], pf1, o[dt], 0, 0, 0);
;     }
; template <int MODE> ...
;     ...
;     for (int st = st_lo; st <= st_hi; st += 2) {
;         if (st + 2 <= st_hi) AT_LOAD(st + 2, ka, va);
;         AT_COMPUTE(sb0, st);
;         if (st + 1 <= st_hi) AT_STORE(sb1, kb, vb);
;         LBAR();
;         if (st + 1 > st_hi) break;
;         if (st + 3 <= st_hi) AT_LOAD(st + 3, kb, vb);
;         AT_COMPUTE(sb1, st + 1);
;         if (st + 2 <= st_hi) AT_STORE(sb0, ka, va);
;         LBAR();
;     }
.Lsel_BdY_resc:
	v_sub_f32_e32 v120, v120, v118
	v_pk_fma_f32 v[104:105], v[104:105], v[114:115], v[120:121] op_sel_hi:[1,0,0]
	v_pk_fma_f32 v[102:103], v[102:103], v[114:115], v[120:121] op_sel_hi:[1,0,0]
	v_exp_f32_e32 v104, v104
	v_exp_f32_e32 v102, v102
	v_exp_f32_e32 v103, v103
	v_exp_f32_e32 v105, v105
	v_pk_fma_f32 v[100:101], v[100:101], v[114:115], v[120:121] op_sel_hi:[1,0,0]
	v_pk_fma_f32 v[98:99], v[98:99], v[114:115], v[120:121] op_sel_hi:[1,0,0]
	v_exp_f32_e32 v100, v100
	v_exp_f32_e32 v98, v98
	v_exp_f32_e32 v99, v99
	v_exp_f32_e32 v101, v101
	v_pk_fma_f32 v[96:97], v[96:97], v[114:115], v[120:121] op_sel_hi:[1,0,0]
	v_pk_fma_f32 v[94:95], v[94:95], v[114:115], v[120:121] op_sel_hi:[1,0,0]
	v_exp_f32_e32 v96, v96
	v_exp_f32_e32 v94, v94
	v_exp_f32_e32 v95, v95
	v_exp_f32_e32 v97, v97
	v_pk_fma_f32 v[92:93], v[92:93], v[114:115], v[120:121] op_sel_hi:[1,0,0]
	v_pk_fma_f32 v[90:91], v[90:91], v[114:115], v[120:121] op_sel_hi:[1,0,0]
	v_exp_f32_e32 v146, v92
	v_exp_f32_e32 v120, v90
	v_exp_f32_e32 v121, v91
	v_exp_f32_e32 v147, v93
	v_pk_add_f32 v[132:133], v[102:103], 0 op_sel_hi:[1,0]
	v_pk_add_f32 v[134:135], v[104:105], 0 op_sel_hi:[1,0]
	v_pk_add_f32 v[132:133], v[98:99], v[132:133]
	v_pk_add_f32 v[134:135], v[100:101], v[134:135]
	v_pk_add_f32 v[132:133], v[94:95], v[132:133]
	v_pk_add_f32 v[134:135], v[96:97], v[134:135]
	v_pk_add_f32 v[92:93], v[120:121], v[132:133]
	v_pk_add_f32 v[90:91], v[146:147], v[134:135]
	v_cvt_pk_bf16_f32 v94, v94, v95
	v_pk_mov_b32 v[132:133], v[92:93], v[90:91] op_sel:[1,0]
	v_mov_b32_e32 v93, v91
	v_pk_add_f32 v[90:91], v[132:133], v[92:93]
	v_cvt_pk_bf16_f32 v92, v98, v99
	v_add_f32_e32 v90, v90, v91
	v_add_f32_e32 v117, v90, v117
	v_cvt_pk_bf16_f32 v90, v102, v103
	v_cvt_pk_bf16_f32 v91, v104, v105
	v_cvt_pk_bf16_f32 v93, v100, v101
	v_cvt_pk_bf16_f32 v95, v96, v97
	v_cvt_pk_bf16_f32 v96, v120, v121
	s_waitcnt lgkmcnt(0)
	v_mfma_f32_16x16x32_bf16 v[46:49], v[86:89], v[90:93], v[46:49]
	v_cvt_pk_bf16_f32 v97, v146, v147
	v_mfma_f32_16x16x32_bf16 v[42:45], v[78:81], v[90:93], v[42:45]
	v_mfma_f32_16x16x32_bf16 v[50:53], v[70:73], v[90:93], v[50:53]
	v_mfma_f32_16x16x32_bf16 v[54:57], v[62:65], v[90:93], v[54:57]
	v_mfma_f32_16x16x32_bf16 v[46:49], v[82:85], v[94:97], v[46:49]
	v_mfma_f32_16x16x32_bf16 v[42:45], v[74:77], v[94:97], v[42:45]
	v_mfma_f32_16x16x32_bf16 v[50:53], v[66:69], v[94:97], v[50:53]
	v_mfma_f32_16x16x32_bf16 v[54:57], v[58:61], v[94:97], v[54:57]
	s_mov_b32 s10, 0
	v_writelane_b32 v255, s10, 60
	s_nop 1
	v_readlane_b32 s10, v255, 61
	s_nop 3
	s_cmp_eq_u32 s10, 0
	s_cbranch_scc1 .Lsel_X_qk
	s_cmp_eq_u32 s10, 2
	s_cbranch_scc1 .Lsel_X_skip_go
	s_branch .Lsel_exit_go
.LBB0_618:
	v_readlane_b32 s10, v255, 60
	s_nop 3
	s_cmp_eq_u32 s10, 0
	s_cbranch_scc1 .Lsel_exit_go
	s_mov_b32 s0, 1
	v_writelane_b32 v255, s0, 61
	s_cmp_eq_u32 s10, 1
	s_cbranch_scc1 .Lsel_BdX
	s_branch .Lsel_BdY
